# v10: as v9 with the FFN-in first-phase waits one count more conservative
# speedup vs baseline: 1.0002x; 1.0002x over previous
.LBB0_491:
	s_ashr_i32 s17, s16, 31
	s_lshl_b64 s[18:19], s[16:17], 19
	s_add_u32 s17, s3, s18
	s_addc_u32 s20, s30, s19
	s_ashr_i32 s15, s14, 31
	s_lshl_b64 s[18:19], s[14:15], 19
	s_add_u32 s15, s31, s18
	s_addc_u32 s23, s34, s19
	s_add_i32 s29, 0, 0x10000
	s_and_b64 s[18:19], s[38:39], exec
	s_cselect_b32 s19, s20, s27
	s_cselect_b32 s18, s17, s26
	s_add_i32 s58, 0, 0x14000
	v_add_u32_e32 v2, s29, v174
	v_add_u32_e32 v85, s58, v174
	ds_read_b128 v[4:7], v2
	ds_read_b128 v[8:11], v2 offset:1024
	ds_read_b128 v[12:15], v2 offset:2048
	ds_read_b128 v[16:19], v2 offset:3072
	ds_read_b128 v[20:23], v85
	ds_read_b128 v[24:27], v85 offset:1024
	ds_read_b128 v[28:31], v85 offset:2048
	ds_read_b128 v[32:35], v85 offset:3072
	s_and_b64 s[20:21], s[38:39], exec
	s_cselect_b32 s21, s23, s25
	s_cselect_b32 s20, s15, s24
	s_add_u32 s54, s26, 0x40080
	s_addc_u32 s55, s27, 0
	s_add_i32 s15, s44, 0xc000
	v_lshl_add_u64 v[68:69], s[54:55], 0, v[0:1]
	s_mov_b32 m0, s15
	s_add_i32 s17, s44, 0xe000
	ds_read_b128 v[36:39], v175
	ds_read_b128 v[40:43], v175 offset:1024
	ds_read_b128 v[44:47], v175 offset:2048
	ds_read_b128 v[48:51], v175 offset:3072
	ds_read_b128 v[52:55], v175 offset:4096
	ds_read_b128 v[56:59], v175 offset:5120
	ds_read_b128 v[60:63], v175 offset:6144
	ds_read_b128 v[64:67], v175 offset:7168
	global_load_lds_dwordx4 v[68:69], off
	v_lshl_add_u64 v[68:69], s[54:55], 0, v[166:167]
	s_mov_b32 m0, s17
	s_nop 0
	global_load_lds_dwordx4 v[68:69], off
	s_waitcnt vmcnt(16)
	s_waitcnt lgkmcnt(0)
	s_setprio 1
	s_barrier
	v_mfma_f32_16x16x32_bf16 v[68:71], v[4:7], v[36:39], 0
	v_mfma_f32_16x16x32_bf16 v[72:75], v[12:15], v[36:39], 0
	v_mfma_f32_16x16x32_bf16 v[80:83], v[12:15], v[44:47], 0
	v_mfma_f32_16x16x32_bf16 v[76:79], v[4:7], v[44:47], 0
	v_mfma_f32_16x16x32_bf16 v[86:89], v[4:7], v[52:55], 0
	v_mfma_f32_16x16x32_bf16 v[68:71], v[8:11], v[40:43], v[68:71]
	v_mfma_f32_16x16x32_bf16 v[72:75], v[16:19], v[40:43], v[72:75]
	v_mfma_f32_16x16x32_bf16 v[140:143], v[8:11], v[48:51], v[76:79]
	v_mfma_f32_16x16x32_bf16 v[80:83], v[16:19], v[48:51], v[80:83]
	v_mfma_f32_16x16x32_bf16 v[144:147], v[8:11], v[56:59], v[86:89]
	v_mfma_f32_16x16x32_bf16 v[92:95], v[12:15], v[52:55], 0
	v_mfma_f32_16x16x32_bf16 v[96:99], v[4:7], v[60:63], 0
	v_mfma_f32_16x16x32_bf16 v[100:103], v[12:15], v[60:63], 0
	v_mfma_f32_16x16x32_bf16 v[92:95], v[16:19], v[56:59], v[92:95]
	v_mfma_f32_16x16x32_bf16 v[96:99], v[8:11], v[64:67], v[96:99]
	v_mfma_f32_16x16x32_bf16 v[100:103], v[16:19], v[64:67], v[100:103]
	v_mfma_f32_16x16x32_bf16 v[104:107], v[20:23], v[36:39], 0
	v_mfma_f32_16x16x32_bf16 v[36:39], v[28:31], v[36:39], 0
	v_mfma_f32_16x16x32_bf16 v[104:107], v[24:27], v[40:43], v[104:107]
	v_mfma_f32_16x16x32_bf16 v[36:39], v[32:35], v[40:43], v[36:39]
	v_mfma_f32_16x16x32_bf16 v[40:43], v[20:23], v[44:47], 0
	v_mfma_f32_16x16x32_bf16 v[44:47], v[28:31], v[44:47], 0
	v_mfma_f32_16x16x32_bf16 v[40:43], v[24:27], v[48:51], v[40:43]
	v_mfma_f32_16x16x32_bf16 v[44:47], v[32:35], v[48:51], v[44:47]
	v_mfma_f32_16x16x32_bf16 v[48:51], v[20:23], v[52:55], 0
	v_mfma_f32_16x16x32_bf16 v[52:55], v[28:31], v[52:55], 0
	v_mfma_f32_16x16x32_bf16 v[48:51], v[24:27], v[56:59], v[48:51]
	v_mfma_f32_16x16x32_bf16 v[52:55], v[32:35], v[56:59], v[52:55]
	v_mfma_f32_16x16x32_bf16 v[56:59], v[20:23], v[60:63], 0
	v_mfma_f32_16x16x32_bf16 v[60:63], v[28:31], v[60:63], 0
	v_mfma_f32_16x16x32_bf16 v[56:59], v[24:27], v[64:67], v[56:59]
	v_mfma_f32_16x16x32_bf16 v[60:63], v[32:35], v[64:67], v[60:63]
	s_barrier
	s_setprio 0
	s_add_i32 s23, s29, s0
	v_lshl_add_u64 v[192:193], s[24:25], 0, v[164:165]
	s_mov_b64 s[60:61], 0x100
	s_add_i32 s53, s23, 0x2000
	v_lshl_add_u64 v[76:77], v[192:193], 0, s[60:61]
	s_mov_b32 m0, s23
	v_lshl_add_u64 v[198:199], s[24:25], 0, v[168:169]
	s_add_u32 s56, s24, 0x40100
	ds_read_b128 v[64:67], v175 offset:16384
	ds_read_b128 v[108:111], v175 offset:17408
	ds_read_b128 v[112:115], v175 offset:18432
	ds_read_b128 v[116:119], v175 offset:19456
	ds_read_b128 v[120:123], v175 offset:20480
	ds_read_b128 v[124:127], v175 offset:21504
	ds_read_b128 v[128:131], v175 offset:22528
	ds_read_b128 v[132:135], v175 offset:23552
	global_load_lds_dwordx4 v[76:77], off
	v_lshl_add_u64 v[76:77], v[198:199], 0, s[60:61]
	s_mov_b32 m0, s53
	s_addc_u32 s57, s25, 0
	s_add_i32 s54, s58, s0
	global_load_lds_dwordx4 v[76:77], off
	v_lshl_add_u64 v[76:77], s[56:57], 0, v[164:165]
	s_mov_b32 m0, s54
	s_add_i32 s55, s54, 0x2000
	global_load_lds_dwordx4 v[76:77], off
	v_lshl_add_u64 v[76:77], s[56:57], 0, v[168:169]
	s_mov_b32 m0, s55
	v_lshl_add_u64 v[228:229], s[26:27], 0, v[0:1]
	global_load_lds_dwordx4 v[76:77], off
	v_lshl_add_u64 v[76:77], v[228:229], 0, s[60:61]
	s_mov_b32 m0, s44
	v_lshl_add_u64 v[234:235], s[26:27], 0, v[166:167]
	global_load_lds_dwordx4 v[76:77], off
	v_lshl_add_u64 v[76:77], v[234:235], 0, s[60:61]
	s_mov_b32 m0, s45
	s_nop 0
	global_load_lds_dwordx4 v[76:77], off
	s_waitcnt vmcnt(16)
	s_waitcnt lgkmcnt(0)
	s_setprio 1
	s_barrier
	v_mfma_f32_16x16x32_bf16 v[136:139], v[4:7], v[64:67], 0
	s_nop 0
	v_mfma_f32_16x16x32_bf16 v[176:179], v[8:11], v[108:111], v[136:139]
	v_mfma_f32_16x16x32_bf16 v[136:139], v[12:15], v[64:67], 0
	s_nop 0
	v_mfma_f32_16x16x32_bf16 v[180:183], v[16:19], v[108:111], v[136:139]
	v_mfma_f32_16x16x32_bf16 v[136:139], v[4:7], v[112:115], 0
	s_nop 0
	v_mfma_f32_16x16x32_bf16 v[184:187], v[8:11], v[116:119], v[136:139]
	v_mfma_f32_16x16x32_bf16 v[136:139], v[12:15], v[112:115], 0
	s_nop 0
	v_mfma_f32_16x16x32_bf16 v[200:203], v[16:19], v[116:119], v[136:139]
	v_mfma_f32_16x16x32_bf16 v[136:139], v[4:7], v[120:123], 0
	v_mfma_f32_16x16x32_bf16 v[4:7], v[4:7], v[128:131], 0
	v_mfma_f32_16x16x32_bf16 v[204:207], v[8:11], v[124:127], v[136:139]
	v_mfma_f32_16x16x32_bf16 v[4:7], v[8:11], v[132:135], v[4:7]
	v_mfma_f32_16x16x32_bf16 v[8:11], v[12:15], v[128:131], 0
	v_mfma_f32_16x16x32_bf16 v[136:139], v[12:15], v[120:123], 0
	v_mfma_f32_16x16x32_bf16 v[12:15], v[16:19], v[132:135], v[8:11]
	v_mfma_f32_16x16x32_bf16 v[208:211], v[16:19], v[124:127], v[136:139]
	v_mfma_f32_16x16x32_bf16 v[8:11], v[20:23], v[64:67], 0
	s_nop 0
	v_mfma_f32_16x16x32_bf16 v[16:19], v[24:27], v[108:111], v[8:11]
	v_mfma_f32_16x16x32_bf16 v[8:11], v[28:31], v[64:67], 0
	s_nop 0
	v_mfma_f32_16x16x32_bf16 v[108:111], v[32:35], v[108:111], v[8:11]
	v_mfma_f32_16x16x32_bf16 v[8:11], v[20:23], v[112:115], 0
	s_nop 0
	v_mfma_f32_16x16x32_bf16 v[212:215], v[24:27], v[116:119], v[8:11]
	v_mfma_f32_16x16x32_bf16 v[8:11], v[28:31], v[112:115], 0
	s_nop 0
	v_mfma_f32_16x16x32_bf16 v[112:115], v[32:35], v[116:119], v[8:11]
	v_mfma_f32_16x16x32_bf16 v[8:11], v[20:23], v[120:123], 0
	s_nop 0
	v_mfma_f32_16x16x32_bf16 v[216:219], v[24:27], v[124:127], v[8:11]
	v_mfma_f32_16x16x32_bf16 v[8:11], v[28:31], v[120:123], 0
	s_nop 0
	v_mfma_f32_16x16x32_bf16 v[220:223], v[32:35], v[124:127], v[8:11]
	v_mfma_f32_16x16x32_bf16 v[8:11], v[20:23], v[128:131], 0
	s_nop 0
	v_mfma_f32_16x16x32_bf16 v[236:239], v[24:27], v[132:135], v[8:11]
	v_mfma_f32_16x16x32_bf16 v[8:11], v[28:31], v[128:131], 0
	s_nop 0
	v_mfma_f32_16x16x32_bf16 v[240:243], v[32:35], v[132:135], v[8:11]
	s_barrier
	s_setprio 0
	s_add_i32 s29, 0, 0x18000
	s_add_i32 s58, 0, 0x1c000
	v_add_u32_e32 v86, s29, v174
	v_add_u32_e32 v87, s58, v174
	ds_read_b128 v[8:11], v86
	ds_read_b128 v[28:31], v86 offset:1024
	ds_read_b128 v[32:35], v86 offset:2048
	ds_read_b128 v[64:67], v86 offset:3072
	ds_read_b128 v[244:247], v87
	ds_read_b128 v[248:251], v87 offset:1024
	ds_read_b128 v[230:233], v87 offset:2048
	ds_read_b128 v[194:197], v87 offset:3072
	s_add_u32 s56, s26, 0x40100
	s_addc_u32 s57, s27, 0
	s_mov_b32 m0, s46
	v_lshl_add_u64 v[116:117], s[56:57], 0, v[0:1]
	ds_read_b128 v[20:23], v175 offset:32768
	ds_read_b128 v[24:27], v175 offset:33792
	ds_read_b128 v[124:127], v175 offset:34816
	ds_read_b128 v[128:131], v175 offset:35840
	ds_read_b128 v[224:227], v175 offset:36864
	ds_read_b128 v[188:191], v175 offset:37888
	ds_read_b128 v[76:79], v175 offset:38912
	ds_read_b128 v[88:91], v175 offset:39936
	global_load_lds_dwordx4 v[116:117], off
	v_lshl_add_u64 v[116:117], s[56:57], 0, v[166:167]
	s_mov_b32 m0, s48
	s_nop 0
	global_load_lds_dwordx4 v[116:117], off
	s_waitcnt vmcnt(8)
	s_waitcnt lgkmcnt(0)
	s_setprio 1
	s_barrier
	v_mfma_f32_16x16x32_bf16 v[68:71], v[8:11], v[20:23], v[68:71]
	v_mfma_f32_16x16x32_bf16 v[152:155], v[28:31], v[24:27], v[68:71]
	v_mfma_f32_16x16x32_bf16 v[68:71], v[32:35], v[20:23], v[72:75]
	v_mfma_f32_16x16x32_bf16 v[148:151], v[64:67], v[24:27], v[68:71]
	v_mfma_f32_16x16x32_bf16 v[68:71], v[8:11], v[124:127], v[140:143]
	v_mfma_f32_16x16x32_bf16 v[136:139], v[28:31], v[128:131], v[68:71]
	v_mfma_f32_16x16x32_bf16 v[68:71], v[32:35], v[124:127], v[80:83]
	v_mfma_f32_16x16x32_bf16 v[132:135], v[64:67], v[128:131], v[68:71]
	v_mfma_f32_16x16x32_bf16 v[68:71], v[8:11], v[224:227], v[144:147]
	v_mfma_f32_16x16x32_bf16 v[120:123], v[28:31], v[188:191], v[68:71]
	v_mfma_f32_16x16x32_bf16 v[68:71], v[32:35], v[224:227], v[92:95]
	v_mfma_f32_16x16x32_bf16 v[116:119], v[64:67], v[188:191], v[68:71]
	v_mfma_f32_16x16x32_bf16 v[68:71], v[8:11], v[76:79], v[96:99]
	v_mfma_f32_16x16x32_bf16 v[72:75], v[28:31], v[88:91], v[68:71]
	v_mfma_f32_16x16x32_bf16 v[68:71], v[32:35], v[76:79], v[100:103]
	v_mfma_f32_16x16x32_bf16 v[68:71], v[64:67], v[88:91], v[68:71]
	v_mfma_f32_16x16x32_bf16 v[80:83], v[244:247], v[20:23], v[104:107]
	v_mfma_f32_16x16x32_bf16 v[20:23], v[230:233], v[20:23], v[36:39]
	v_mfma_f32_16x16x32_bf16 v[156:159], v[194:197], v[24:27], v[20:23]
	v_mfma_f32_16x16x32_bf16 v[20:23], v[244:247], v[124:127], v[40:43]
	v_mfma_f32_16x16x32_bf16 v[144:147], v[248:251], v[128:131], v[20:23]
	v_mfma_f32_16x16x32_bf16 v[20:23], v[230:233], v[124:127], v[44:47]
	v_mfma_f32_16x16x32_bf16 v[140:143], v[194:197], v[128:131], v[20:23]
	v_mfma_f32_16x16x32_bf16 v[20:23], v[244:247], v[224:227], v[48:51]
	v_mfma_f32_16x16x32_bf16 v[128:131], v[248:251], v[188:191], v[20:23]
	v_mfma_f32_16x16x32_bf16 v[20:23], v[230:233], v[224:227], v[52:55]
	v_mfma_f32_16x16x32_bf16 v[124:127], v[194:197], v[188:191], v[20:23]
	v_mfma_f32_16x16x32_bf16 v[20:23], v[244:247], v[76:79], v[56:59]
	v_mfma_f32_16x16x32_bf16 v[160:163], v[248:251], v[24:27], v[80:83]
	v_mfma_f32_16x16x32_bf16 v[80:83], v[248:251], v[88:91], v[20:23]
	v_mfma_f32_16x16x32_bf16 v[20:23], v[230:233], v[76:79], v[60:63]
	v_mfma_f32_16x16x32_bf16 v[76:79], v[194:197], v[88:91], v[20:23]
	s_barrier
	s_setprio 0
	s_add_i32 s56, s29, s0
	s_add_i32 s57, s56, 0x2000
	s_nop 2
	v_lshl_add_u64 v[20:21], v[192:193], 0, s[84:85]
	s_mov_b32 m0, s56
	s_add_u32 s60, s24, 0x40180
	ds_read_b128 v[44:47], v175 offset:49152
	ds_read_b128 v[48:51], v175 offset:50176
	ds_read_b128 v[88:91], v175 offset:51200
	ds_read_b128 v[92:95], v175 offset:52224
	ds_read_b128 v[96:99], v175 offset:53248
	ds_read_b128 v[100:103], v175 offset:54272
	ds_read_b128 v[104:107], v175 offset:55296
	ds_read_b128 v[188:191], v175 offset:56320
	global_load_lds_dwordx4 v[20:21], off
	v_lshl_add_u64 v[20:21], v[198:199], 0, s[84:85]
	s_mov_b32 m0, s57
	s_addc_u32 s61, s25, 0
	s_add_i32 s58, s58, s0
	global_load_lds_dwordx4 v[20:21], off
	v_lshl_add_u64 v[20:21], s[60:61], 0, v[164:165]
	s_mov_b32 m0, s58
	s_add_i32 s59, s58, 0x2000
	global_load_lds_dwordx4 v[20:21], off
	v_lshl_add_u64 v[20:21], s[60:61], 0, v[168:169]
	s_mov_b32 m0, s59
	s_nop 0
	global_load_lds_dwordx4 v[20:21], off
	v_lshl_add_u64 v[20:21], v[228:229], 0, s[84:85]
	s_mov_b32 m0, s49
	s_nop 0
	global_load_lds_dwordx4 v[20:21], off
	v_lshl_add_u64 v[20:21], v[234:235], 0, s[84:85]
	s_mov_b32 m0, s50
	s_nop 0
	global_load_lds_dwordx4 v[20:21], off
	s_waitcnt vmcnt(8)
	s_waitcnt lgkmcnt(0)
	s_setprio 1
	s_barrier
	v_mfma_f32_16x16x32_bf16 v[20:23], v[8:11], v[44:47], v[176:179]
	v_mfma_f32_16x16x32_bf16 v[56:59], v[28:31], v[48:51], v[20:23]
	v_mfma_f32_16x16x32_bf16 v[20:23], v[32:35], v[44:47], v[180:183]
	v_mfma_f32_16x16x32_bf16 v[52:55], v[64:67], v[48:51], v[20:23]
	v_mfma_f32_16x16x32_bf16 v[20:23], v[8:11], v[88:91], v[184:187]
	v_mfma_f32_16x16x32_bf16 v[40:43], v[28:31], v[92:95], v[20:23]
	v_mfma_f32_16x16x32_bf16 v[20:23], v[32:35], v[88:91], v[200:203]
	v_mfma_f32_16x16x32_bf16 v[36:39], v[64:67], v[92:95], v[20:23]
	v_mfma_f32_16x16x32_bf16 v[20:23], v[8:11], v[96:99], v[204:207]
	v_mfma_f32_16x16x32_bf16 v[4:7], v[8:11], v[104:107], v[4:7]
	v_mfma_f32_16x16x32_bf16 v[24:27], v[28:31], v[100:103], v[20:23]
	v_mfma_f32_16x16x32_bf16 v[20:23], v[32:35], v[96:99], v[208:211]
	v_mfma_f32_16x16x32_bf16 v[8:11], v[28:31], v[188:191], v[4:7]
	v_mfma_f32_16x16x32_bf16 v[4:7], v[32:35], v[104:107], v[12:15]
	v_mfma_f32_16x16x32_bf16 v[20:23], v[64:67], v[100:103], v[20:23]
	v_mfma_f32_16x16x32_bf16 v[4:7], v[64:67], v[188:191], v[4:7]
	v_mfma_f32_16x16x32_bf16 v[12:15], v[244:247], v[44:47], v[16:19]
	v_mfma_f32_16x16x32_bf16 v[64:67], v[248:251], v[48:51], v[12:15]
	v_mfma_f32_16x16x32_bf16 v[12:15], v[230:233], v[44:47], v[108:111]
	v_mfma_f32_16x16x32_bf16 v[60:63], v[194:197], v[48:51], v[12:15]
	v_mfma_f32_16x16x32_bf16 v[12:15], v[244:247], v[88:91], v[212:215]
	v_mfma_f32_16x16x32_bf16 v[48:51], v[248:251], v[92:95], v[12:15]
	v_mfma_f32_16x16x32_bf16 v[12:15], v[230:233], v[88:91], v[112:115]
	v_mfma_f32_16x16x32_bf16 v[44:47], v[194:197], v[92:95], v[12:15]
	v_mfma_f32_16x16x32_bf16 v[12:15], v[244:247], v[96:99], v[216:219]
	v_mfma_f32_16x16x32_bf16 v[32:35], v[248:251], v[100:103], v[12:15]
	v_mfma_f32_16x16x32_bf16 v[12:15], v[230:233], v[96:99], v[220:223]
	v_mfma_f32_16x16x32_bf16 v[28:31], v[194:197], v[100:103], v[12:15]
	v_mfma_f32_16x16x32_bf16 v[12:15], v[244:247], v[104:107], v[236:239]
	v_mfma_f32_16x16x32_bf16 v[16:19], v[248:251], v[188:191], v[12:15]
	v_mfma_f32_16x16x32_bf16 v[12:15], v[230:233], v[104:107], v[240:243]
	v_mfma_f32_16x16x32_bf16 v[12:15], v[194:197], v[188:191], v[12:15]
	s_barrier
	s_setprio 0
	s_lshl_b32 s28, s28, 11
	s_and_b32 s28, s28, 0x800
	s_add_i32 s60, s28, 0
	s_add_i32 s60, s60, 0x25a00
	s_lshl_b32 s28, s43, 2
	s_add_i32 s28, s60, s28
	s_add_u32 s26, s26, 0x40180
	s_addc_u32 s27, s27, 0
	v_mbcnt_lo_u32_b32 v88, -1, 0
	v_mbcnt_hi_u32_b32 v88, -1, v88
	s_add_u32 s61, s24, 0x200
	v_lshl_add_u32 v88, v88, 2, s28
	s_addc_u32 s62, s25, 0
	s_mov_b32 s76, 0
	s_waitcnt vmcnt(8)
	ds_write_b32 v88, v84

.LBB0_1647:
	s_ashr_i32 s17, s16, 31
	s_lshl_b64 s[18:19], s[16:17], 19
	s_add_u32 s17, s3, s18
	s_addc_u32 s20, s30, s19
	s_ashr_i32 s15, s14, 31
	s_lshl_b64 s[18:19], s[14:15], 19
	s_add_u32 s15, s31, s18
	s_addc_u32 s23, s34, s19
	s_add_i32 s29, 0, 0x10000
	s_and_b64 s[18:19], s[38:39], exec
	s_cselect_b32 s19, s20, s27
	s_cselect_b32 s18, s17, s26
	s_add_i32 s58, 0, 0x14000
	v_add_u32_e32 v2, s29, v174
	v_add_u32_e32 v85, s58, v174
	ds_read_b128 v[4:7], v2
	ds_read_b128 v[8:11], v2 offset:1024
	ds_read_b128 v[12:15], v2 offset:2048
	ds_read_b128 v[16:19], v2 offset:3072
	ds_read_b128 v[20:23], v85
	ds_read_b128 v[24:27], v85 offset:1024
	ds_read_b128 v[28:31], v85 offset:2048
	ds_read_b128 v[32:35], v85 offset:3072
	s_and_b64 s[20:21], s[38:39], exec
	s_cselect_b32 s21, s23, s25
	s_cselect_b32 s20, s15, s24
	s_add_u32 s54, s26, 0x40080
	s_addc_u32 s55, s27, 0
	s_add_i32 s15, s44, 0xc000
	v_lshl_add_u64 v[68:69], s[54:55], 0, v[0:1]
	s_mov_b32 m0, s15
	s_add_i32 s17, s44, 0xe000
	ds_read_b128 v[36:39], v175
	ds_read_b128 v[40:43], v175 offset:1024
	ds_read_b128 v[44:47], v175 offset:2048
	ds_read_b128 v[48:51], v175 offset:3072
	ds_read_b128 v[52:55], v175 offset:4096
	ds_read_b128 v[56:59], v175 offset:5120
	ds_read_b128 v[60:63], v175 offset:6144
	ds_read_b128 v[64:67], v175 offset:7168
	global_load_lds_dwordx4 v[68:69], off
	v_lshl_add_u64 v[68:69], s[54:55], 0, v[166:167]
	s_mov_b32 m0, s17
	s_nop 0
	global_load_lds_dwordx4 v[68:69], off
	s_waitcnt vmcnt(16)
	s_waitcnt lgkmcnt(0)
	s_setprio 1
	s_barrier
	v_mfma_f32_16x16x32_bf16 v[68:71], v[4:7], v[36:39], 0
	v_mfma_f32_16x16x32_bf16 v[72:75], v[12:15], v[36:39], 0
	v_mfma_f32_16x16x32_bf16 v[76:79], v[4:7], v[44:47], 0
	v_mfma_f32_16x16x32_bf16 v[80:83], v[12:15], v[44:47], 0
	v_mfma_f32_16x16x32_bf16 v[68:71], v[8:11], v[40:43], v[68:71]
	v_mfma_f32_16x16x32_bf16 v[72:75], v[16:19], v[40:43], v[72:75]
	v_mfma_f32_16x16x32_bf16 v[76:79], v[8:11], v[48:51], v[76:79]
	v_mfma_f32_16x16x32_bf16 v[80:83], v[16:19], v[48:51], v[80:83]
	v_mfma_f32_16x16x32_bf16 v[86:89], v[4:7], v[52:55], 0
	v_mfma_f32_16x16x32_bf16 v[92:95], v[12:15], v[52:55], 0
	v_mfma_f32_16x16x32_bf16 v[96:99], v[4:7], v[60:63], 0
	v_mfma_f32_16x16x32_bf16 v[100:103], v[12:15], v[60:63], 0
	v_mfma_f32_16x16x32_bf16 v[88:91], v[8:11], v[56:59], v[86:89]
	v_mfma_f32_16x16x32_bf16 v[92:95], v[16:19], v[56:59], v[92:95]
	v_mfma_f32_16x16x32_bf16 v[96:99], v[8:11], v[64:67], v[96:99]
	v_mfma_f32_16x16x32_bf16 v[100:103], v[16:19], v[64:67], v[100:103]
	v_mfma_f32_16x16x32_bf16 v[104:107], v[20:23], v[36:39], 0
	v_mfma_f32_16x16x32_bf16 v[36:39], v[28:31], v[36:39], 0
	v_mfma_f32_16x16x32_bf16 v[104:107], v[24:27], v[40:43], v[104:107]
	v_mfma_f32_16x16x32_bf16 v[140:143], v[32:35], v[40:43], v[36:39]
	v_mfma_f32_16x16x32_bf16 v[40:43], v[20:23], v[44:47], 0
	v_mfma_f32_16x16x32_bf16 v[44:47], v[28:31], v[44:47], 0
	v_mfma_f32_16x16x32_bf16 v[144:147], v[24:27], v[48:51], v[40:43]
	v_mfma_f32_16x16x32_bf16 v[44:47], v[32:35], v[48:51], v[44:47]
	v_mfma_f32_16x16x32_bf16 v[48:51], v[20:23], v[52:55], 0
	v_mfma_f32_16x16x32_bf16 v[52:55], v[28:31], v[52:55], 0
	v_mfma_f32_16x16x32_bf16 v[48:51], v[24:27], v[56:59], v[48:51]
	v_mfma_f32_16x16x32_bf16 v[52:55], v[32:35], v[56:59], v[52:55]
	v_mfma_f32_16x16x32_bf16 v[56:59], v[20:23], v[60:63], 0
	v_mfma_f32_16x16x32_bf16 v[60:63], v[28:31], v[60:63], 0
	v_mfma_f32_16x16x32_bf16 v[56:59], v[24:27], v[64:67], v[56:59]
	v_mfma_f32_16x16x32_bf16 v[60:63], v[32:35], v[64:67], v[60:63]
	s_barrier
	s_setprio 0
	s_add_i32 s23, s29, s0
	v_lshl_add_u64 v[252:253], s[24:25], 0, v[164:165]
	s_mov_b64 s[60:61], 0x100
	s_add_i32 s53, s23, 0x2000
	v_lshl_add_u64 v[86:87], v[252:253], 0, s[60:61]
	s_mov_b32 m0, s23
	v_lshl_add_u64 v[36:37], s[24:25], 0, v[168:169]
	s_add_u32 s56, s24, 0x40100
	ds_read_b128 v[64:67], v175 offset:16384
	ds_read_b128 v[108:111], v175 offset:17408
	ds_read_b128 v[112:115], v175 offset:18432
	ds_read_b128 v[116:119], v175 offset:19456
	ds_read_b128 v[120:123], v175 offset:20480
	ds_read_b128 v[124:127], v175 offset:21504
	ds_read_b128 v[128:131], v175 offset:22528
	ds_read_b128 v[132:135], v175 offset:23552
	global_load_lds_dwordx4 v[86:87], off
	v_lshl_add_u64 v[38:39], v[36:37], 0, s[60:61]
	s_mov_b32 m0, s53
	s_addc_u32 s57, s25, 0
	s_add_i32 s54, s58, s0
	global_load_lds_dwordx4 v[38:39], off
	v_lshl_add_u64 v[38:39], s[56:57], 0, v[164:165]
	s_mov_b32 m0, s54
	s_add_i32 s55, s54, 0x2000
	global_load_lds_dwordx4 v[38:39], off
	v_lshl_add_u64 v[38:39], s[56:57], 0, v[168:169]
	s_mov_b32 m0, s55
	v_lshl_add_u64 v[40:41], s[26:27], 0, v[166:167]
	global_load_lds_dwordx4 v[38:39], off
	v_lshl_add_u64 v[38:39], s[26:27], 0, v[0:1]
	v_lshl_add_u64 v[86:87], v[38:39], 0, s[60:61]
	s_mov_b32 m0, s44
	v_lshl_add_u64 v[42:43], v[40:41], 0, s[60:61]
	global_load_lds_dwordx4 v[86:87], off
	s_mov_b32 m0, s45
	s_nop 0
	global_load_lds_dwordx4 v[42:43], off
	s_waitcnt vmcnt(16)
	s_waitcnt lgkmcnt(0)
	s_setprio 1
	s_barrier
	v_mfma_f32_16x16x32_bf16 v[136:139], v[4:7], v[64:67], 0
	s_nop 0
	v_mfma_f32_16x16x32_bf16 v[176:179], v[8:11], v[108:111], v[136:139]
	v_mfma_f32_16x16x32_bf16 v[136:139], v[12:15], v[64:67], 0
	s_nop 0
	v_mfma_f32_16x16x32_bf16 v[180:183], v[16:19], v[108:111], v[136:139]
	v_mfma_f32_16x16x32_bf16 v[136:139], v[4:7], v[112:115], 0
	s_nop 0
	v_mfma_f32_16x16x32_bf16 v[184:187], v[8:11], v[116:119], v[136:139]
	v_mfma_f32_16x16x32_bf16 v[136:139], v[12:15], v[112:115], 0
	s_nop 0
	v_mfma_f32_16x16x32_bf16 v[188:191], v[16:19], v[116:119], v[136:139]
	v_mfma_f32_16x16x32_bf16 v[136:139], v[4:7], v[120:123], 0
	v_mfma_f32_16x16x32_bf16 v[4:7], v[4:7], v[128:131], 0
	v_mfma_f32_16x16x32_bf16 v[192:195], v[8:11], v[124:127], v[136:139]
	v_mfma_f32_16x16x32_bf16 v[4:7], v[8:11], v[132:135], v[4:7]
	v_mfma_f32_16x16x32_bf16 v[8:11], v[12:15], v[128:131], 0
	v_mfma_f32_16x16x32_bf16 v[136:139], v[12:15], v[120:123], 0
	v_mfma_f32_16x16x32_bf16 v[12:15], v[16:19], v[132:135], v[8:11]
	v_mfma_f32_16x16x32_bf16 v[200:203], v[16:19], v[124:127], v[136:139]
	v_mfma_f32_16x16x32_bf16 v[8:11], v[20:23], v[64:67], 0
	s_nop 0
	v_mfma_f32_16x16x32_bf16 v[16:19], v[24:27], v[108:111], v[8:11]
	v_mfma_f32_16x16x32_bf16 v[8:11], v[28:31], v[64:67], 0
	s_nop 0
	v_mfma_f32_16x16x32_bf16 v[108:111], v[32:35], v[108:111], v[8:11]
	v_mfma_f32_16x16x32_bf16 v[8:11], v[20:23], v[112:115], 0
	s_nop 0
	v_mfma_f32_16x16x32_bf16 v[204:207], v[24:27], v[116:119], v[8:11]
	v_mfma_f32_16x16x32_bf16 v[8:11], v[28:31], v[112:115], 0
	s_nop 0
	v_mfma_f32_16x16x32_bf16 v[112:115], v[32:35], v[116:119], v[8:11]
	v_mfma_f32_16x16x32_bf16 v[8:11], v[20:23], v[120:123], 0
	s_nop 0
	v_mfma_f32_16x16x32_bf16 v[208:211], v[24:27], v[124:127], v[8:11]
	v_mfma_f32_16x16x32_bf16 v[8:11], v[28:31], v[120:123], 0
	s_nop 0
	v_mfma_f32_16x16x32_bf16 v[212:215], v[32:35], v[124:127], v[8:11]
	v_mfma_f32_16x16x32_bf16 v[8:11], v[20:23], v[128:131], 0
	s_nop 0
	v_mfma_f32_16x16x32_bf16 v[216:219], v[24:27], v[132:135], v[8:11]
	v_mfma_f32_16x16x32_bf16 v[8:11], v[28:31], v[128:131], 0
	s_nop 0
	v_mfma_f32_16x16x32_bf16 v[220:223], v[32:35], v[132:135], v[8:11]
	s_barrier
	s_setprio 0
	s_add_i32 s29, 0, 0x18000
	s_add_i32 s58, 0, 0x1c000
	v_add_u32_e32 v86, s29, v174
	v_add_u32_e32 v87, s58, v174
	ds_read_b128 v[8:11], v86
	ds_read_b128 v[28:31], v86 offset:1024
	ds_read_b128 v[32:35], v86 offset:2048
	ds_read_b128 v[64:67], v86 offset:3072
	ds_read_b128 v[224:227], v87
	ds_read_b128 v[228:231], v87 offset:1024
	ds_read_b128 v[232:235], v87 offset:2048
	ds_read_b128 v[236:239], v87 offset:3072
	s_add_u32 s56, s26, 0x40100
	s_addc_u32 s57, s27, 0
	s_mov_b32 m0, s46
	v_lshl_add_u64 v[42:43], s[56:57], 0, v[0:1]
	ds_read_b128 v[20:23], v175 offset:32768
	ds_read_b128 v[24:27], v175 offset:33792
	ds_read_b128 v[124:127], v175 offset:34816
	ds_read_b128 v[128:131], v175 offset:35840
	ds_read_b128 v[240:243], v175 offset:36864
	ds_read_b128 v[244:247], v175 offset:37888
	ds_read_b128 v[248:251], v175 offset:38912
	ds_read_b128 v[196:199], v175 offset:39936
	global_load_lds_dwordx4 v[42:43], off
	v_lshl_add_u64 v[42:43], s[56:57], 0, v[166:167]
	s_mov_b32 m0, s48
	s_nop 0
	global_load_lds_dwordx4 v[42:43], off
	s_waitcnt vmcnt(8)
	s_waitcnt lgkmcnt(0)
	s_setprio 1
	s_barrier
	v_mfma_f32_16x16x32_bf16 v[68:71], v[8:11], v[20:23], v[68:71]
	v_mfma_f32_16x16x32_bf16 v[152:155], v[28:31], v[24:27], v[68:71]
	v_mfma_f32_16x16x32_bf16 v[68:71], v[32:35], v[20:23], v[72:75]
	v_mfma_f32_16x16x32_bf16 v[148:151], v[64:67], v[24:27], v[68:71]
	v_mfma_f32_16x16x32_bf16 v[68:71], v[8:11], v[124:127], v[76:79]
	v_mfma_f32_16x16x32_bf16 v[136:139], v[28:31], v[128:131], v[68:71]
	v_mfma_f32_16x16x32_bf16 v[68:71], v[32:35], v[124:127], v[80:83]
	v_mfma_f32_16x16x32_bf16 v[132:135], v[64:67], v[128:131], v[68:71]
	v_mfma_f32_16x16x32_bf16 v[68:71], v[8:11], v[240:243], v[88:91]
	v_mfma_f32_16x16x32_bf16 v[120:123], v[28:31], v[244:247], v[68:71]
	v_mfma_f32_16x16x32_bf16 v[68:71], v[32:35], v[240:243], v[92:95]
	v_mfma_f32_16x16x32_bf16 v[116:119], v[64:67], v[244:247], v[68:71]
	v_mfma_f32_16x16x32_bf16 v[68:71], v[8:11], v[248:251], v[96:99]
	v_mfma_f32_16x16x32_bf16 v[72:75], v[28:31], v[196:199], v[68:71]
	v_mfma_f32_16x16x32_bf16 v[68:71], v[32:35], v[248:251], v[100:103]
	v_mfma_f32_16x16x32_bf16 v[68:71], v[64:67], v[196:199], v[68:71]
	v_mfma_f32_16x16x32_bf16 v[76:79], v[224:227], v[20:23], v[104:107]
	v_mfma_f32_16x16x32_bf16 v[20:23], v[232:235], v[20:23], v[140:143]
	v_mfma_f32_16x16x32_bf16 v[156:159], v[236:239], v[24:27], v[20:23]
	v_mfma_f32_16x16x32_bf16 v[20:23], v[224:227], v[124:127], v[144:147]
	v_mfma_f32_16x16x32_bf16 v[144:147], v[228:231], v[128:131], v[20:23]
	v_mfma_f32_16x16x32_bf16 v[20:23], v[232:235], v[124:127], v[44:47]
	v_mfma_f32_16x16x32_bf16 v[140:143], v[236:239], v[128:131], v[20:23]
	v_mfma_f32_16x16x32_bf16 v[20:23], v[224:227], v[240:243], v[48:51]
	v_mfma_f32_16x16x32_bf16 v[128:131], v[228:231], v[244:247], v[20:23]
	v_mfma_f32_16x16x32_bf16 v[20:23], v[232:235], v[240:243], v[52:55]
	v_mfma_f32_16x16x32_bf16 v[124:127], v[236:239], v[244:247], v[20:23]
	v_mfma_f32_16x16x32_bf16 v[20:23], v[224:227], v[248:251], v[56:59]
	v_mfma_f32_16x16x32_bf16 v[80:83], v[228:231], v[196:199], v[20:23]
	v_mfma_f32_16x16x32_bf16 v[20:23], v[232:235], v[248:251], v[60:63]
	v_mfma_f32_16x16x32_bf16 v[160:163], v[228:231], v[24:27], v[76:79]
	v_mfma_f32_16x16x32_bf16 v[76:79], v[236:239], v[196:199], v[20:23]
	s_barrier
	s_setprio 0
	s_add_i32 s56, s29, s0
	s_add_i32 s57, s56, 0x2000
	s_nop 1
	v_lshl_add_u64 v[20:21], v[252:253], 0, s[84:85]
	s_mov_b32 m0, s56
	s_add_u32 s60, s24, 0x40180
	ds_read_b128 v[44:47], v175 offset:49152
	ds_read_b128 v[48:51], v175 offset:50176
	ds_read_b128 v[88:91], v175 offset:51200
	ds_read_b128 v[92:95], v175 offset:52224
	ds_read_b128 v[96:99], v175 offset:53248
	ds_read_b128 v[100:103], v175 offset:54272
	ds_read_b128 v[104:107], v175 offset:55296
	ds_read_b128 v[196:199], v175 offset:56320
	global_load_lds_dwordx4 v[20:21], off
	v_lshl_add_u64 v[20:21], v[36:37], 0, s[84:85]
	s_mov_b32 m0, s57
	s_addc_u32 s61, s25, 0
	s_add_i32 s58, s58, s0
	global_load_lds_dwordx4 v[20:21], off
	v_lshl_add_u64 v[20:21], s[60:61], 0, v[164:165]
	s_mov_b32 m0, s58
	s_add_i32 s59, s58, 0x2000
	global_load_lds_dwordx4 v[20:21], off
	v_lshl_add_u64 v[20:21], s[60:61], 0, v[168:169]
	s_mov_b32 m0, s59
	s_nop 0
	global_load_lds_dwordx4 v[20:21], off
	v_lshl_add_u64 v[20:21], v[38:39], 0, s[84:85]
	s_mov_b32 m0, s49
	s_nop 0
	global_load_lds_dwordx4 v[20:21], off
	v_lshl_add_u64 v[20:21], v[40:41], 0, s[84:85]
	s_mov_b32 m0, s50
	s_nop 0
	global_load_lds_dwordx4 v[20:21], off
	s_waitcnt vmcnt(8)
	s_waitcnt lgkmcnt(0)
	s_setprio 1
	s_barrier
	v_mfma_f32_16x16x32_bf16 v[20:23], v[8:11], v[44:47], v[176:179]
	v_mfma_f32_16x16x32_bf16 v[56:59], v[28:31], v[48:51], v[20:23]
	v_mfma_f32_16x16x32_bf16 v[20:23], v[32:35], v[44:47], v[180:183]
	v_mfma_f32_16x16x32_bf16 v[52:55], v[64:67], v[48:51], v[20:23]
	v_mfma_f32_16x16x32_bf16 v[20:23], v[8:11], v[88:91], v[184:187]
	v_mfma_f32_16x16x32_bf16 v[40:43], v[28:31], v[92:95], v[20:23]
	v_mfma_f32_16x16x32_bf16 v[20:23], v[32:35], v[88:91], v[188:191]
	v_mfma_f32_16x16x32_bf16 v[36:39], v[64:67], v[92:95], v[20:23]
	v_mfma_f32_16x16x32_bf16 v[20:23], v[8:11], v[96:99], v[192:195]
	v_mfma_f32_16x16x32_bf16 v[4:7], v[8:11], v[104:107], v[4:7]
	v_mfma_f32_16x16x32_bf16 v[24:27], v[28:31], v[100:103], v[20:23]
	v_mfma_f32_16x16x32_bf16 v[20:23], v[32:35], v[96:99], v[200:203]
	v_mfma_f32_16x16x32_bf16 v[8:11], v[28:31], v[196:199], v[4:7]
	v_mfma_f32_16x16x32_bf16 v[4:7], v[32:35], v[104:107], v[12:15]
	v_mfma_f32_16x16x32_bf16 v[20:23], v[64:67], v[100:103], v[20:23]
	v_mfma_f32_16x16x32_bf16 v[4:7], v[64:67], v[196:199], v[4:7]
	v_mfma_f32_16x16x32_bf16 v[12:15], v[224:227], v[44:47], v[16:19]
	v_mfma_f32_16x16x32_bf16 v[64:67], v[228:231], v[48:51], v[12:15]
	v_mfma_f32_16x16x32_bf16 v[12:15], v[232:235], v[44:47], v[108:111]
	v_mfma_f32_16x16x32_bf16 v[60:63], v[236:239], v[48:51], v[12:15]
	v_mfma_f32_16x16x32_bf16 v[12:15], v[224:227], v[88:91], v[204:207]
	v_mfma_f32_16x16x32_bf16 v[48:51], v[228:231], v[92:95], v[12:15]
	v_mfma_f32_16x16x32_bf16 v[12:15], v[232:235], v[88:91], v[112:115]
	v_mfma_f32_16x16x32_bf16 v[44:47], v[236:239], v[92:95], v[12:15]
	v_mfma_f32_16x16x32_bf16 v[12:15], v[224:227], v[96:99], v[208:211]
	v_mfma_f32_16x16x32_bf16 v[32:35], v[228:231], v[100:103], v[12:15]
	v_mfma_f32_16x16x32_bf16 v[12:15], v[232:235], v[96:99], v[212:215]
	v_mfma_f32_16x16x32_bf16 v[28:31], v[236:239], v[100:103], v[12:15]
	v_mfma_f32_16x16x32_bf16 v[12:15], v[224:227], v[104:107], v[216:219]
	v_mfma_f32_16x16x32_bf16 v[16:19], v[228:231], v[196:199], v[12:15]
	v_mfma_f32_16x16x32_bf16 v[12:15], v[232:235], v[104:107], v[220:223]
	v_mfma_f32_16x16x32_bf16 v[12:15], v[236:239], v[196:199], v[12:15]
	s_barrier
	s_setprio 0
	s_lshl_b32 s28, s28, 11
	s_and_b32 s28, s28, 0x800
	s_add_i32 s60, s28, 0
	s_add_i32 s60, s60, 0x25a00
	s_lshl_b32 s28, s43, 2
	s_add_i32 s28, s60, s28
	s_add_u32 s26, s26, 0x40180
	s_addc_u32 s27, s27, 0
	v_mbcnt_lo_u32_b32 v88, -1, 0
	v_mbcnt_hi_u32_b32 v88, -1, v88
	s_add_u32 s61, s24, 0x200
	v_lshl_add_u32 v88, v88, 2, s28
	s_addc_u32 s62, s25, 0
	s_mov_b32 s76, 0
	s_waitcnt vmcnt(8)
	ds_write_b32 v88, v84
